# v19 + attention part-3 (MLA context-query wave units) moved from the last 8 workgroups (pair consumers) to workgroups 32-39 (early-finishing producers)
# baseline (speedup 1.0000x reference)
.LBB0_885:
	s_and_b64 vcc, exec, s[38:39]
	s_cbranch_vccz .LBB0_904
	s_load_dword s0, s[84:85], 0x10
	v_readlane_b32 s2, v252, 34
	s_waitcnt lgkmcnt(0)
	s_lshr_b32 s0, s0, 16
	s_cmp_lg_u32 s0, 0
	s_cselect_b64 s[0:1], -1, 0
	s_cmp_lg_u64 s[0:1], 0
	s_addc_u32 s0, s63, 0
	s_movk_i32 s1, 0x100
	s_sub_i32 s1, s2, s1
	s_cmp_gt_u32 s0, 7
	v_readlane_b32 s2, v253, 56
	s_cselect_b32 s0, s1, s2
	s_cmp_gt_u32 s0, 63
	v_readlane_b32 s3, v253, 57
	s_cbranch_scc1 .LBB0_904
	v_readlane_b32 s2, v251, 37
	v_readlane_b32 s3, v251, 38
	s_lshl_b32 s1, s0, 5
	s_nop 0
	v_lshl_add_u64 v[188:189], s[2:3], 0, v[152:153]
	v_readlane_b32 s2, v252, 15
	v_readlane_b32 s3, v252, 16
	s_nop 1
	v_lshl_add_u64 v[190:191], s[2:3], 0, v[152:153]
	s_branch .LBB0_889
